# GEMM accumulator zero-init with 64 v_mov_b64 instead of 128 v_mov_b32 before each unit's K-loop (six live instances); stacked on stack17
# speedup vs baseline: 1.0067x; 1.0067x over previous
; template <class Epi, class Sched, bool ALIGN_EPI = false, bool SP2 = false>
; __device__ __forceinline__ void gemm_phase(PG8_LAS unsigned char* lds, const Gemm g, const Sched& S, const Epi& E) {
;     ...
;         const bool has_next = S.next(ui + 1, nxt);
;         const char* nA = has_next ? (const char*)g.A + (size_t)nxt.pm * tstep : cA; const char* nB = has_next ? (const char*)g.Bt + (size_t)nxt.pn * tstep : cB;
;     ...
; #pragma unroll
;         for (int a = 0; a < 2; ++a)
; #pragma unroll
;             for (int b = 0; b < 2; ++b)
; #pragma unroll
;                 for (int m = 0; m < 4; ++m)
; #pragma unroll
;                     for (int n = 0; n < 2; ++n) acc[a][b][m][n] = (f32x4){0.f, 0.f, 0.f, 0.f};
.LBB0_163:
	s_ashr_i32 s51, s50, 31
	s_lshl_b64 s[36:37], s[50:51], 19
	s_add_u32 s62, s2, s36
	s_addc_u32 s63, s14, s37
	s_and_b64 s[36:37], s[40:41], exec
	s_cselect_b32 s36, s63, s65
	s_cselect_b32 s37, s62, s64
	s_ashr_i32 s53, s52, 31
	s_lshl_b64 s[66:67], s[52:53], 19
	s_add_u32 s66, s15, s66
	s_addc_u32 s67, s16, s67
	s_and_b64 s[72:73], s[40:41], exec
	s_cselect_b32 s51, s67, s59
	s_cselect_b32 s53, s66, s58
	s_add_u32 s72, s64, 0x40080
	s_addc_u32 s73, s65, 0
	s_add_u32 s92, s58, 0x100
	v_mov_b64_e32 v[0:1], 0
	s_addc_u32 s93, s59, 0
	s_mov_b32 s94, -2
	v_mov_b64_e32 v[2:3], 0
	v_mov_b64_e32 v[4:5], 0
	v_mov_b64_e32 v[6:7], 0
	v_mov_b64_e32 v[8:9], 0
	v_mov_b64_e32 v[10:11], 0
	v_mov_b64_e32 v[12:13], 0
	v_mov_b64_e32 v[14:15], 0
	v_mov_b64_e32 v[16:17], 0
	v_mov_b64_e32 v[18:19], 0
	v_mov_b64_e32 v[20:21], 0
	v_mov_b64_e32 v[22:23], 0
	v_mov_b64_e32 v[24:25], 0
	v_mov_b64_e32 v[26:27], 0
	v_mov_b64_e32 v[28:29], 0
	v_mov_b64_e32 v[30:31], 0
	v_mov_b64_e32 v[32:33], 0
	v_mov_b64_e32 v[34:35], 0
	v_mov_b64_e32 v[36:37], 0
	v_mov_b64_e32 v[38:39], 0
	v_mov_b64_e32 v[40:41], 0
	v_mov_b64_e32 v[42:43], 0
	v_mov_b64_e32 v[44:45], 0
	v_mov_b64_e32 v[46:47], 0
	v_mov_b64_e32 v[48:49], 0
	v_mov_b64_e32 v[50:51], 0
	v_mov_b64_e32 v[52:53], 0
	v_mov_b64_e32 v[54:55], 0
	v_mov_b64_e32 v[56:57], 0
	v_mov_b64_e32 v[58:59], 0
	v_mov_b64_e32 v[60:61], 0
	v_mov_b64_e32 v[62:63], 0
	v_mov_b64_e32 v[64:65], 0
	v_mov_b64_e32 v[66:67], 0
	v_mov_b64_e32 v[68:69], 0
	v_mov_b64_e32 v[70:71], 0
	v_mov_b64_e32 v[72:73], 0
	v_mov_b64_e32 v[74:75], 0
	v_mov_b64_e32 v[76:77], 0
	v_mov_b64_e32 v[78:79], 0
	v_mov_b64_e32 v[80:81], 0
	v_mov_b64_e32 v[82:83], 0
	v_mov_b64_e32 v[84:85], 0
	v_mov_b64_e32 v[86:87], 0
	v_mov_b64_e32 v[88:89], 0
	v_mov_b64_e32 v[90:91], 0
	v_mov_b64_e32 v[92:93], 0
	v_mov_b64_e32 v[94:95], 0
	v_mov_b64_e32 v[96:97], 0
	v_mov_b64_e32 v[98:99], 0
	v_mov_b64_e32 v[100:101], 0
	v_mov_b64_e32 v[102:103], 0
	v_mov_b64_e32 v[104:105], 0
	v_mov_b64_e32 v[106:107], 0
	v_mov_b64_e32 v[108:109], 0
	v_mov_b64_e32 v[110:111], 0
	v_mov_b64_e32 v[112:113], 0
	v_mov_b64_e32 v[114:115], 0
	v_mov_b64_e32 v[116:117], 0
	v_mov_b64_e32 v[118:119], 0
	v_mov_b64_e32 v[120:121], 0
	v_mov_b64_e32 v[122:123], 0
	v_mov_b64_e32 v[124:125], 0
	v_mov_b64_e32 v[126:127], 0

; template <class Epi, class Sched, bool ALIGN_EPI = false, bool SP2 = false>
; __device__ __forceinline__ void gemm_phase(PG8_LAS unsigned char* lds, const Gemm g, const Sched& S, const Epi& E) {
;     ...
; #pragma unroll
;         for (int a = 0; a < 2; ++a)
; #pragma unroll
;             for (int b = 0; b < 2; ++b)
; #pragma unroll
;                 for (int m = 0; m < 4; ++m)
; #pragma unroll
;                     for (int n = 0; n < 2; ++n) acc[a][b][m][n] = (f32x4){0.f, 0.f, 0.f, 0.f};
.LBB0_563:
	s_ashr_i32 s67, s66, 31
	s_lshl_b64 s[36:37], s[66:67], 19
	s_add_u32 s64, s2, s36
	s_addc_u32 s65, s25, s37
	s_and_b64 s[36:37], s[40:41], exec
	s_cselect_b32 s36, s65, s93
	s_cselect_b32 s37, s64, s92
	s_ashr_i32 s73, s72, 31
	s_lshl_b64 s[84:85], s[72:73], 19
	s_add_u32 s96, s70, s84
	s_addc_u32 s97, s16, s85
	s_and_b64 s[84:85], s[40:41], exec
	s_cselect_b32 s67, s97, s59
	s_cselect_b32 s73, s96, s58
	s_add_u32 vcc_lo, s92, 0x40080
	s_addc_u32 vcc_hi, s93, 0
	s_add_u32 s88, s58, 0x100
	v_mov_b64_e32 v[0:1], 0
	s_addc_u32 s94, s59, 0
	s_mov_b32 s84, -2
	v_mov_b64_e32 v[2:3], 0
	v_mov_b64_e32 v[4:5], 0
	v_mov_b64_e32 v[6:7], 0
	v_mov_b64_e32 v[16:17], 0
	v_mov_b64_e32 v[18:19], 0
	v_mov_b64_e32 v[20:21], 0
	v_mov_b64_e32 v[22:23], 0
	v_mov_b64_e32 v[32:33], 0
	v_mov_b64_e32 v[34:35], 0
	v_mov_b64_e32 v[36:37], 0
	v_mov_b64_e32 v[38:39], 0
	v_mov_b64_e32 v[48:49], 0
	v_mov_b64_e32 v[50:51], 0
	v_mov_b64_e32 v[52:53], 0
	v_mov_b64_e32 v[54:55], 0
	v_mov_b64_e32 v[8:9], 0
	v_mov_b64_e32 v[10:11], 0
	v_mov_b64_e32 v[12:13], 0
	v_mov_b64_e32 v[14:15], 0
	v_mov_b64_e32 v[24:25], 0
	v_mov_b64_e32 v[26:27], 0
	v_mov_b64_e32 v[28:29], 0
	v_mov_b64_e32 v[30:31], 0
	v_mov_b64_e32 v[40:41], 0
	v_mov_b64_e32 v[42:43], 0
	v_mov_b64_e32 v[44:45], 0
	v_mov_b64_e32 v[46:47], 0
	v_mov_b64_e32 v[56:57], 0
	v_mov_b64_e32 v[58:59], 0
	v_mov_b64_e32 v[60:61], 0
	v_mov_b64_e32 v[62:63], 0
	v_mov_b64_e32 v[64:65], 0
	v_mov_b64_e32 v[66:67], 0
	v_mov_b64_e32 v[68:69], 0
	v_mov_b64_e32 v[70:71], 0
	v_mov_b64_e32 v[80:81], 0
	v_mov_b64_e32 v[82:83], 0
	v_mov_b64_e32 v[84:85], 0
	v_mov_b64_e32 v[86:87], 0
	v_mov_b64_e32 v[96:97], 0
	v_mov_b64_e32 v[98:99], 0
	v_mov_b64_e32 v[100:101], 0
	v_mov_b64_e32 v[102:103], 0
	v_mov_b64_e32 v[112:113], 0
	v_mov_b64_e32 v[114:115], 0
	v_mov_b64_e32 v[116:117], 0
	v_mov_b64_e32 v[118:119], 0
	v_mov_b64_e32 v[72:73], 0
	v_mov_b64_e32 v[74:75], 0
	v_mov_b64_e32 v[76:77], 0
	v_mov_b64_e32 v[78:79], 0
	v_mov_b64_e32 v[88:89], 0
	v_mov_b64_e32 v[90:91], 0
	v_mov_b64_e32 v[92:93], 0
	v_mov_b64_e32 v[94:95], 0
	v_mov_b64_e32 v[104:105], 0
	v_mov_b64_e32 v[106:107], 0
	v_mov_b64_e32 v[108:109], 0
	v_mov_b64_e32 v[110:111], 0
	v_mov_b64_e32 v[120:121], 0
	v_mov_b64_e32 v[122:123], 0
	v_mov_b64_e32 v[124:125], 0
	v_mov_b64_e32 v[126:127], 0

; template <class Epi, class Sched, bool ALIGN_EPI = false, bool SP2 = false>
; __device__ __forceinline__ void gemm_phase(PG8_LAS unsigned char* lds, const Gemm g, const Sched& S, const Epi& E) {
;     ...
; #pragma unroll
;         for (int a = 0; a < 2; ++a)
; #pragma unroll
;             for (int b = 0; b < 2; ++b)
; #pragma unroll
;                 for (int m = 0; m < 4; ++m)
; #pragma unroll
;                     for (int n = 0; n < 2; ++n) acc[a][b][m][n] = (f32x4){0.f, 0.f, 0.f, 0.f};
.LBB0_597:
	s_ashr_i32 s93, s92, 31
	s_lshl_b64 s[36:37], s[92:93], 19
	s_add_u32 s44, s2, s36
	s_addc_u32 s45, s25, s37
	s_and_b64 s[36:37], s[40:41], exec
	s_cselect_b32 s35, s45, s65
	s_cselect_b32 s36, s44, s64
	s_ashr_i32 s97, s96, 31
	s_lshl_b64 s[62:63], s[96:97], 19
	s_add_u32 s62, s70, s62
	s_addc_u32 s63, s16, s63
	s_and_b64 s[84:85], s[40:41], exec
	s_cselect_b32 s37, s63, s59
	s_cselect_b32 s43, s62, s58
	s_add_u32 vcc_lo, s64, 0x40080
	s_addc_u32 vcc_hi, s65, 0
	s_add_u32 s88, s58, 0x100
	v_mov_b64_e32 v[0:1], 0
	s_addc_u32 s93, s59, 0
	s_mov_b32 s94, -2
	v_mov_b64_e32 v[2:3], 0
	v_mov_b64_e32 v[4:5], 0
	v_mov_b64_e32 v[6:7], 0
	v_mov_b64_e32 v[16:17], 0
	v_mov_b64_e32 v[18:19], 0
	v_mov_b64_e32 v[20:21], 0
	v_mov_b64_e32 v[22:23], 0
	v_mov_b64_e32 v[32:33], 0
	v_mov_b64_e32 v[34:35], 0
	v_mov_b64_e32 v[36:37], 0
	v_mov_b64_e32 v[38:39], 0
	v_mov_b64_e32 v[40:41], 0
	v_mov_b64_e32 v[42:43], 0
	v_mov_b64_e32 v[48:49], 0
	v_mov_b64_e32 v[50:51], 0
	v_mov_b64_e32 v[8:9], 0
	v_mov_b64_e32 v[10:11], 0
	v_mov_b64_e32 v[12:13], 0
	v_mov_b64_e32 v[14:15], 0
	v_mov_b64_e32 v[24:25], 0
	v_mov_b64_e32 v[26:27], 0
	v_mov_b64_e32 v[28:29], 0
	v_mov_b64_e32 v[30:31], 0
	v_mov_b64_e32 v[44:45], 0
	v_mov_b64_e32 v[46:47], 0
	v_mov_b64_e32 v[52:53], 0
	v_mov_b64_e32 v[54:55], 0
	v_mov_b64_e32 v[56:57], 0
	v_mov_b64_e32 v[58:59], 0
	v_mov_b64_e32 v[60:61], 0
	v_mov_b64_e32 v[62:63], 0
	v_mov_b64_e32 v[80:81], 0
	v_mov_b64_e32 v[82:83], 0
	v_mov_b64_e32 v[84:85], 0
	v_mov_b64_e32 v[86:87], 0
	v_mov_b64_e32 v[88:89], 0
	v_mov_b64_e32 v[90:91], 0
	v_mov_b64_e32 v[96:97], 0
	v_mov_b64_e32 v[98:99], 0
	v_mov_b64_e32 v[112:113], 0
	v_mov_b64_e32 v[114:115], 0
	v_mov_b64_e32 v[116:117], 0
	v_mov_b64_e32 v[118:119], 0
	v_mov_b64_e32 v[120:121], 0
	v_mov_b64_e32 v[122:123], 0
	v_mov_b64_e32 v[130:131], 0
	v_mov_b64_e32 v[132:133], 0
	v_mov_b64_e32 v[92:93], 0
	v_mov_b64_e32 v[94:95], 0
	v_mov_b64_e32 v[100:101], 0
	v_mov_b64_e32 v[102:103], 0
	v_mov_b64_e32 v[104:105], 0
	v_mov_b64_e32 v[106:107], 0
	v_mov_b64_e32 v[108:109], 0
	v_mov_b64_e32 v[110:111], 0
	v_mov_b64_e32 v[124:125], 0
	v_mov_b64_e32 v[126:127], 0
	v_mov_b64_e32 v[134:135], 0
	v_mov_b64_e32 v[136:137], 0
	v_mov_b64_e32 v[138:139], 0
	v_mov_b64_e32 v[140:141], 0
	v_mov_b64_e32 v[142:143], 0
	v_mov_b64_e32 v[144:145], 0

; template <class Epi, class Sched, bool ALIGN_EPI = false, bool SP2 = false>
; __device__ __forceinline__ void gemm_phase(PG8_LAS unsigned char* lds, const Gemm g, const Sched& S, const Epi& E) {
;     ...
; #pragma unroll
;         for (int a = 0; a < 2; ++a)
; #pragma unroll
;             for (int b = 0; b < 2; ++b)
; #pragma unroll
;                 for (int m = 0; m < 4; ++m)
; #pragma unroll
;                     for (int n = 0; n < 2; ++n) acc[a][b][m][n] = (f32x4){0.f, 0.f, 0.f, 0.f};
.LBB0_812:
	s_ashr_i32 s49, s48, 31
	s_lshl_b64 s[28:29], s[48:49], 19
	s_add_u32 s52, s2, s28
	s_addc_u32 s53, s14, s29
	s_and_b64 s[28:29], s[38:39], exec
	s_cselect_b32 s28, s53, s65
	s_cselect_b32 s29, s52, s64
	s_ashr_i32 s51, s50, 31
	s_lshl_b64 s[30:31], s[50:51], 19
	s_add_u32 s62, s15, s30
	s_addc_u32 s63, s16, s31
	s_and_b64 s[30:31], s[38:39], exec
	s_cselect_b32 s30, s63, s59
	s_cselect_b32 s31, s62, s58
	s_add_u32 s66, s64, 0x40080
	s_addc_u32 s67, s65, 0
	s_add_u32 s34, s58, 0x100
	v_mov_b64_e32 v[0:1], 0
	s_addc_u32 s35, s59, 0
	s_mov_b32 s36, -2
	v_mov_b64_e32 v[2:3], 0
	v_mov_b64_e32 v[8:9], 0
	v_mov_b64_e32 v[10:11], 0
	v_mov_b64_e32 v[16:17], 0
	v_mov_b64_e32 v[18:19], 0
	v_mov_b64_e32 v[24:25], 0
	v_mov_b64_e32 v[26:27], 0
	v_mov_b64_e32 v[32:33], 0
	v_mov_b64_e32 v[34:35], 0
	v_mov_b64_e32 v[40:41], 0
	v_mov_b64_e32 v[42:43], 0
	v_mov_b64_e32 v[48:49], 0
	v_mov_b64_e32 v[50:51], 0
	v_mov_b64_e32 v[56:57], 0
	v_mov_b64_e32 v[58:59], 0
	v_mov_b64_e32 v[4:5], 0
	v_mov_b64_e32 v[6:7], 0
	v_mov_b64_e32 v[12:13], 0
	v_mov_b64_e32 v[14:15], 0
	v_mov_b64_e32 v[20:21], 0
	v_mov_b64_e32 v[22:23], 0
	v_mov_b64_e32 v[28:29], 0
	v_mov_b64_e32 v[30:31], 0
	v_mov_b64_e32 v[36:37], 0
	v_mov_b64_e32 v[38:39], 0
	v_mov_b64_e32 v[44:45], 0
	v_mov_b64_e32 v[46:47], 0
	v_mov_b64_e32 v[52:53], 0
	v_mov_b64_e32 v[54:55], 0
	v_mov_b64_e32 v[60:61], 0
	v_mov_b64_e32 v[62:63], 0
	v_mov_b64_e32 v[64:65], 0
	v_mov_b64_e32 v[66:67], 0
	v_mov_b64_e32 v[72:73], 0
	v_mov_b64_e32 v[74:75], 0
	v_mov_b64_e32 v[80:81], 0
	v_mov_b64_e32 v[82:83], 0
	v_mov_b64_e32 v[88:89], 0
	v_mov_b64_e32 v[90:91], 0
	v_mov_b64_e32 v[96:97], 0
	v_mov_b64_e32 v[98:99], 0
	v_mov_b64_e32 v[104:105], 0
	v_mov_b64_e32 v[106:107], 0
	v_mov_b64_e32 v[112:113], 0
	v_mov_b64_e32 v[114:115], 0
	v_mov_b64_e32 v[120:121], 0
	v_mov_b64_e32 v[122:123], 0
	v_mov_b64_e32 v[68:69], 0
	v_mov_b64_e32 v[70:71], 0
	v_mov_b64_e32 v[76:77], 0
	v_mov_b64_e32 v[78:79], 0
	v_mov_b64_e32 v[84:85], 0
	v_mov_b64_e32 v[86:87], 0
	v_mov_b64_e32 v[92:93], 0
	v_mov_b64_e32 v[94:95], 0
	v_mov_b64_e32 v[100:101], 0
	v_mov_b64_e32 v[102:103], 0
	v_mov_b64_e32 v[108:109], 0
	v_mov_b64_e32 v[110:111], 0
	v_mov_b64_e32 v[116:117], 0
	v_mov_b64_e32 v[118:119], 0
	v_mov_b64_e32 v[124:125], 0
	v_mov_b64_e32 v[126:127], 0

; template <class Epi, class Sched, bool ALIGN_EPI = false, bool SP2 = false>
; __device__ __forceinline__ void gemm_phase(PG8_LAS unsigned char* lds, const Gemm g, const Sched& S, const Epi& E) {
;     ...
; #pragma unroll
;         for (int a = 0; a < 2; ++a)
; #pragma unroll
;             for (int b = 0; b < 2; ++b)
; #pragma unroll
;                 for (int m = 0; m < 4; ++m)
; #pragma unroll
;                     for (int n = 0; n < 2; ++n) acc[a][b][m][n] = (f32x4){0.f, 0.f, 0.f, 0.f};
.LBB0_956:
	s_add_u32 s36, s46, 0x100
	v_mov_b64_e32 v[0:1], 0
	s_addc_u32 s37, s47, 0
	s_mov_b32 s70, -2
	v_mov_b64_e32 v[2:3], 0
	v_mov_b64_e32 v[4:5], 0
	v_mov_b64_e32 v[6:7], 0
	v_mov_b64_e32 v[16:17], 0
	v_mov_b64_e32 v[18:19], 0
	v_mov_b64_e32 v[20:21], 0
	v_mov_b64_e32 v[22:23], 0
	v_mov_b64_e32 v[32:33], 0
	v_mov_b64_e32 v[34:35], 0
	v_mov_b64_e32 v[36:37], 0
	v_mov_b64_e32 v[38:39], 0
	v_mov_b64_e32 v[48:49], 0
	v_mov_b64_e32 v[50:51], 0
	v_mov_b64_e32 v[52:53], 0
	v_mov_b64_e32 v[54:55], 0
	v_mov_b64_e32 v[8:9], 0
	v_mov_b64_e32 v[10:11], 0
	v_mov_b64_e32 v[12:13], 0
	v_mov_b64_e32 v[14:15], 0
	v_mov_b64_e32 v[24:25], 0
	v_mov_b64_e32 v[26:27], 0
	v_mov_b64_e32 v[28:29], 0
	v_mov_b64_e32 v[30:31], 0
	v_mov_b64_e32 v[40:41], 0
	v_mov_b64_e32 v[42:43], 0
	v_mov_b64_e32 v[44:45], 0
	v_mov_b64_e32 v[46:47], 0
	v_mov_b64_e32 v[56:57], 0
	v_mov_b64_e32 v[58:59], 0
	v_mov_b64_e32 v[60:61], 0
	v_mov_b64_e32 v[62:63], 0
	v_mov_b64_e32 v[64:65], 0
	v_mov_b64_e32 v[66:67], 0
	v_mov_b64_e32 v[68:69], 0
	v_mov_b64_e32 v[70:71], 0
	v_mov_b64_e32 v[80:81], 0
	v_mov_b64_e32 v[82:83], 0
	v_mov_b64_e32 v[84:85], 0
	v_mov_b64_e32 v[86:87], 0
	v_mov_b64_e32 v[96:97], 0
	v_mov_b64_e32 v[98:99], 0
	v_mov_b64_e32 v[100:101], 0
	v_mov_b64_e32 v[102:103], 0
	v_mov_b64_e32 v[112:113], 0
	v_mov_b64_e32 v[114:115], 0
	v_mov_b64_e32 v[116:117], 0
	v_mov_b64_e32 v[118:119], 0
	v_mov_b64_e32 v[72:73], 0
	v_mov_b64_e32 v[74:75], 0
	v_mov_b64_e32 v[76:77], 0
	v_mov_b64_e32 v[78:79], 0
	v_mov_b64_e32 v[88:89], 0
	v_mov_b64_e32 v[90:91], 0
	v_mov_b64_e32 v[92:93], 0
	v_mov_b64_e32 v[94:95], 0
	v_mov_b64_e32 v[104:105], 0
	v_mov_b64_e32 v[106:107], 0
	v_mov_b64_e32 v[108:109], 0
	v_mov_b64_e32 v[110:111], 0
	v_mov_b64_e32 v[120:121], 0
	v_mov_b64_e32 v[122:123], 0
	v_mov_b64_e32 v[124:125], 0
	v_mov_b64_e32 v[126:127], 0

; template <class Epi, class Sched, bool ALIGN_EPI = false, bool SP2 = false>
; __device__ __forceinline__ void gemm_phase(PG8_LAS unsigned char* lds, const Gemm g, const Sched& S, const Epi& E) {
;     ...
; #pragma unroll
;         for (int a = 0; a < 2; ++a)
; #pragma unroll
;             for (int b = 0; b < 2; ++b)
; #pragma unroll
;                 for (int m = 0; m < 4; ++m)
; #pragma unroll
;                     for (int n = 0; n < 2; ++n) acc[a][b][m][n] = (f32x4){0.f, 0.f, 0.f, 0.f};
.LBB0_994:
	s_add_u32 s36, s46, 0x100
	v_mov_b64_e32 v[0:1], 0
	s_addc_u32 s37, s47, 0
	s_mov_b32 s84, -2
	v_mov_b64_e32 v[2:3], 0
	v_mov_b64_e32 v[4:5], 0
	v_mov_b64_e32 v[6:7], 0
	v_mov_b64_e32 v[16:17], 0
	v_mov_b64_e32 v[18:19], 0
	v_mov_b64_e32 v[20:21], 0
	v_mov_b64_e32 v[22:23], 0
	v_mov_b64_e32 v[32:33], 0
	v_mov_b64_e32 v[34:35], 0
	v_mov_b64_e32 v[36:37], 0
	v_mov_b64_e32 v[38:39], 0
	v_mov_b64_e32 v[48:49], 0
	v_mov_b64_e32 v[50:51], 0
	v_mov_b64_e32 v[52:53], 0
	v_mov_b64_e32 v[54:55], 0
	v_mov_b64_e32 v[8:9], 0
	v_mov_b64_e32 v[10:11], 0
	v_mov_b64_e32 v[12:13], 0
	v_mov_b64_e32 v[14:15], 0
	v_mov_b64_e32 v[24:25], 0
	v_mov_b64_e32 v[26:27], 0
	v_mov_b64_e32 v[28:29], 0
	v_mov_b64_e32 v[30:31], 0
	v_mov_b64_e32 v[40:41], 0
	v_mov_b64_e32 v[42:43], 0
	v_mov_b64_e32 v[44:45], 0
	v_mov_b64_e32 v[46:47], 0
	v_mov_b64_e32 v[56:57], 0
	v_mov_b64_e32 v[58:59], 0
	v_mov_b64_e32 v[60:61], 0
	v_mov_b64_e32 v[62:63], 0
	v_mov_b64_e32 v[64:65], 0
	v_mov_b64_e32 v[66:67], 0
	v_mov_b64_e32 v[68:69], 0
	v_mov_b64_e32 v[70:71], 0
	v_mov_b64_e32 v[80:81], 0
	v_mov_b64_e32 v[82:83], 0
	v_mov_b64_e32 v[84:85], 0
	v_mov_b64_e32 v[86:87], 0
	v_mov_b64_e32 v[96:97], 0
	v_mov_b64_e32 v[98:99], 0
	v_mov_b64_e32 v[100:101], 0
	v_mov_b64_e32 v[102:103], 0
	v_mov_b64_e32 v[112:113], 0
	v_mov_b64_e32 v[114:115], 0
	v_mov_b64_e32 v[116:117], 0
	v_mov_b64_e32 v[118:119], 0
	v_mov_b64_e32 v[72:73], 0
	v_mov_b64_e32 v[74:75], 0
	v_mov_b64_e32 v[76:77], 0
	v_mov_b64_e32 v[78:79], 0
	v_mov_b64_e32 v[88:89], 0
	v_mov_b64_e32 v[90:91], 0
	v_mov_b64_e32 v[92:93], 0
	v_mov_b64_e32 v[94:95], 0
	v_mov_b64_e32 v[104:105], 0
	v_mov_b64_e32 v[106:107], 0
	v_mov_b64_e32 v[108:109], 0
	v_mov_b64_e32 v[110:111], 0
	v_mov_b64_e32 v[120:121], 0
	v_mov_b64_e32 v[122:123], 0
	v_mov_b64_e32 v[124:125], 0
	v_mov_b64_e32 v[126:127], 0
